# code placement: the five GEMM K-loop heads aligned to 64 bytes (asm guide 9.3)
# speedup vs baseline: 1.0009x; 1.0009x over previous
.LBB0_137:
	s_ashr_i32 s49, s48, 31
	s_lshl_b64 s[22:23], s[48:49], 20
	s_add_u32 s52, s26, s22
	s_addc_u32 s53, s27, s23
	s_and_b64 s[0:1], s[0:1], exec
	s_cselect_b32 s22, s53, s7
	s_cselect_b32 s23, s52, s6
	s_add_u32 s0, s12, 0x80080
	s_addc_u32 s1, s13, 0
	s_add_u32 s38, s6, 0x100
	v_mov_b64_e32 v[2:3], 0
	s_addc_u32 s39, s7, 0
	s_mov_b32 s49, -2
	v_mov_b64_e32 v[4:5], 0
	v_mov_b64_e32 v[6:7], 0
	v_mov_b64_e32 v[8:9], 0
	v_mov_b64_e32 v[10:11], 0
	v_mov_b64_e32 v[12:13], 0
	v_mov_b64_e32 v[14:15], 0
	v_mov_b64_e32 v[16:17], 0
	v_mov_b64_e32 v[18:19], 0
	v_mov_b64_e32 v[20:21], 0
	v_mov_b64_e32 v[22:23], 0
	v_mov_b64_e32 v[24:25], 0
	v_mov_b64_e32 v[26:27], 0
	v_mov_b64_e32 v[28:29], 0
	v_mov_b64_e32 v[30:31], 0
	v_mov_b64_e32 v[32:33], 0
	v_mov_b64_e32 v[34:35], 0
	v_mov_b64_e32 v[36:37], 0
	v_mov_b64_e32 v[38:39], 0
	v_mov_b64_e32 v[40:41], 0
	v_mov_b64_e32 v[42:43], 0
	v_mov_b64_e32 v[44:45], 0
	v_mov_b64_e32 v[46:47], 0
	v_mov_b64_e32 v[48:49], 0
	v_mov_b64_e32 v[50:51], 0
	v_mov_b64_e32 v[52:53], 0
	v_mov_b64_e32 v[54:55], 0
	v_mov_b64_e32 v[56:57], 0
	v_mov_b64_e32 v[58:59], 0
	v_mov_b64_e32 v[60:61], 0
	v_mov_b64_e32 v[62:63], 0
	v_mov_b64_e32 v[64:65], 0
	v_mov_b64_e32 v[66:67], 0
	v_mov_b64_e32 v[68:69], 0
	v_mov_b64_e32 v[70:71], 0
	v_mov_b64_e32 v[72:73], 0
	v_mov_b64_e32 v[74:75], 0
	v_mov_b64_e32 v[76:77], 0
	v_mov_b64_e32 v[78:79], 0
	v_mov_b64_e32 v[80:81], 0
	v_mov_b64_e32 v[82:83], 0
	v_mov_b64_e32 v[84:85], 0
	v_mov_b64_e32 v[86:87], 0
	v_mov_b64_e32 v[88:89], 0
	v_mov_b64_e32 v[90:91], 0
	v_mov_b64_e32 v[92:93], 0
	v_mov_b64_e32 v[94:95], 0
	v_mov_b64_e32 v[96:97], 0
	v_mov_b64_e32 v[98:99], 0
	v_mov_b64_e32 v[100:101], 0
	v_mov_b64_e32 v[102:103], 0
	v_mov_b64_e32 v[104:105], 0
	v_mov_b64_e32 v[106:107], 0
	v_mov_b64_e32 v[108:109], 0
	v_mov_b64_e32 v[110:111], 0
	v_mov_b64_e32 v[112:113], 0
	v_mov_b64_e32 v[114:115], 0
	v_mov_b64_e32 v[116:117], 0
	v_mov_b64_e32 v[118:119], 0
	v_mov_b64_e32 v[120:121], 0
	v_mov_b64_e32 v[122:123], 0
	v_mov_b64_e32 v[124:125], 0
	v_mov_b64_e32 v[126:127], 0
	v_mov_b64_e32 v[128:129], 0
	v_add_u32_e32 v224, 0x10000, v149
	v_add_u32_e32 v225, 0x14000, v149
	v_add_u32_e32 v226, 0x18000, v149
	v_add_u32_e32 v227, 0x1c000, v149
	.p2align	6

.LBB0_726:
	s_xor_b64 s[6:7], s[26:27], -1
	s_add_i32 vcc_lo, s14, 32
	s_lshl_b64 s[12:13], s[14:15], 7
	s_mov_b64 s[22:23], 0x1f00
	v_mov_b64_e32 v[130:131], v[158:159]
	v_mov_b64_e32 v[132:133], v[156:157]
	s_mov_b64 s[26:27], s[8:9]
	s_mov_b64 s[30:31], s[0:1]
	v_add_u32_e32 v224, 0x10000, v149
	v_add_u32_e32 v225, 0x14000, v149
	v_add_u32_e32 v226, 0x18000, v149
	v_add_u32_e32 v227, 0x1c000, v149
	.p2align	6

.LBB0_806:
	s_add_u32 s79, s26, 0x100
	s_addc_u32 s80, s27, 0
	s_ashr_i32 s9, s8, 31
	s_lshl_b64 s[12:13], s[8:9], 20
	s_add_u32 s12, s38, s12
	s_addc_u32 s13, s39, s13
	s_and_b64 s[30:31], s[44:45], exec
	s_cselect_b32 s9, s13, s27
	s_cselect_b32 s44, s12, s26
	s_add_u32 s26, s6, 0x80080
	s_addc_u32 s27, s7, 0
	v_lshl_add_u64 v[140:141], s[26:27], 0, v[136:137]
	v_lshl_add_u64 v[142:143], s[26:27], 0, v[138:139]
	s_mov_b32 s45, -2
	s_mov_b64 s[26:27], 0
	v_add_u32_e32 v224, 0x10000, v144
	v_add_u32_e32 v225, 0x14000, v144
	v_add_u32_e32 v226, 0x18000, v144
	v_add_u32_e32 v227, 0x1c000, v144
	.p2align	6

.LBB0_938:
	s_ashr_i32 s23, s22, 31
	s_lshl_b64 s[28:29], s[22:23], 20
	s_add_u32 s28, s8, s28
	s_addc_u32 s29, s9, s29
	s_and_b64 s[38:39], s[42:43], exec
	s_cselect_b32 s23, s29, s37
	s_cselect_b32 s42, s28, s36
	s_add_u32 s30, s30, 0x80080
	s_addc_u32 s31, s31, 0
	s_add_u32 s43, s36, 0x100
	v_mov_b64_e32 v[2:3], 0
	s_addc_u32 s67, s37, 0
	s_mov_b32 s68, -2
	v_mov_b64_e32 v[4:5], 0
	v_mov_b64_e32 v[6:7], 0
	v_mov_b64_e32 v[8:9], 0
	v_mov_b64_e32 v[10:11], 0
	v_mov_b64_e32 v[12:13], 0
	v_mov_b64_e32 v[14:15], 0
	v_mov_b64_e32 v[16:17], 0
	v_mov_b64_e32 v[18:19], 0
	v_mov_b64_e32 v[20:21], 0
	v_mov_b64_e32 v[22:23], 0
	v_mov_b64_e32 v[24:25], 0
	v_mov_b64_e32 v[26:27], 0
	v_mov_b64_e32 v[28:29], 0
	v_mov_b64_e32 v[30:31], 0
	v_mov_b64_e32 v[32:33], 0
	v_mov_b64_e32 v[34:35], 0
	v_mov_b64_e32 v[36:37], 0
	v_mov_b64_e32 v[38:39], 0
	v_mov_b64_e32 v[40:41], 0
	v_mov_b64_e32 v[42:43], 0
	v_mov_b64_e32 v[44:45], 0
	v_mov_b64_e32 v[46:47], 0
	v_mov_b64_e32 v[48:49], 0
	v_mov_b64_e32 v[50:51], 0
	v_mov_b64_e32 v[52:53], 0
	v_mov_b64_e32 v[54:55], 0
	v_mov_b64_e32 v[56:57], 0
	v_mov_b64_e32 v[58:59], 0
	v_mov_b64_e32 v[60:61], 0
	v_mov_b64_e32 v[62:63], 0
	v_mov_b64_e32 v[64:65], 0
	v_mov_b64_e32 v[66:67], 0
	v_mov_b64_e32 v[68:69], 0
	v_mov_b64_e32 v[70:71], 0
	v_mov_b64_e32 v[72:73], 0
	v_mov_b64_e32 v[74:75], 0
	v_mov_b64_e32 v[76:77], 0
	v_mov_b64_e32 v[78:79], 0
	v_mov_b64_e32 v[80:81], 0
	v_mov_b64_e32 v[82:83], 0
	v_mov_b64_e32 v[84:85], 0
	v_mov_b64_e32 v[86:87], 0
	v_mov_b64_e32 v[88:89], 0
	v_mov_b64_e32 v[90:91], 0
	v_mov_b64_e32 v[92:93], 0
	v_mov_b64_e32 v[94:95], 0
	v_mov_b64_e32 v[96:97], 0
	v_mov_b64_e32 v[98:99], 0
	v_mov_b64_e32 v[100:101], 0
	v_mov_b64_e32 v[102:103], 0
	v_mov_b64_e32 v[104:105], 0
	v_mov_b64_e32 v[106:107], 0
	v_mov_b64_e32 v[108:109], 0
	v_mov_b64_e32 v[110:111], 0
	v_mov_b64_e32 v[112:113], 0
	v_mov_b64_e32 v[114:115], 0
	v_mov_b64_e32 v[116:117], 0
	v_mov_b64_e32 v[118:119], 0
	v_mov_b64_e32 v[120:121], 0
	v_mov_b64_e32 v[122:123], 0
	v_mov_b64_e32 v[124:125], 0
	v_mov_b64_e32 v[126:127], 0
	v_mov_b64_e32 v[128:129], 0
	v_add_u32_e32 v224, 0x10000, v140
	v_add_u32_e32 v225, 0x14000, v140
	v_add_u32_e32 v226, 0x18000, v140
	v_add_u32_e32 v227, 0x1c000, v140
	.p2align	6

.LBB0_1083:
	s_add_u32 s42, s22, 0x100
	s_addc_u32 s43, s23, 0
	s_add_u32 s22, s6, 0x158080
	s_addc_u32 s23, s7, 0
	v_lshl_add_u64 v[142:143], s[22:23], 0, v[138:139]
	v_lshl_add_u64 v[144:145], s[22:23], 0, v[140:141]
	s_mov_b32 s78, -2
	s_mov_b64 s[22:23], 0
	v_add_u32_e32 v224, 0x10000, v146
	v_add_u32_e32 v225, 0x14000, v146
	v_add_u32_e32 v226, 0x18000, v146
	v_add_u32_e32 v227, 0x1c000, v146
	.p2align	6
